# EpiRes sample-row K-piece epilogue: 4 gate loads in flight per row group with counted vmcnt (w_out + FFN-down)
# baseline (speedup 1.0000x reference)
.LBB0_1162:
	s_ashr_i32 s17, s59, 31
	s_lshr_b32 s17, s17, 30
	s_add_i32 s17, s59, s17
	s_ashr_i32 s26, s17, 2
	s_ashr_i32 s27, s26, 31
	s_lshl_b64 s[26:27], s[26:27], 21
	s_add_u32 s26, s50, s26
	s_addc_u32 s27, s51, s27
	s_lshl_b32 s17, s54, 8
	v_add_u32_e32 v68, s17, v222
	v_ashrrev_i32_e32 v66, 2, v68
	v_or_b32_e32 v69, 8, v66
	v_mov_b64_e32 v[66:67], s[10:11]
	v_lshl_add_u64 v[64:65], s[26:27], 0, v[160:161]
	v_mad_i64_i32 v[70:71], s[26:27], v69, s33, v[66:67]
	v_ashrrev_i32_e32 v69, 31, v68
	v_lshl_add_u64 v[74:75], v[70:71], 0, v[160:161]
	v_lshlrev_b64 v[70:71], 12, v[68:69]
	v_lshl_add_u64 v[84:85], v[64:65], 0, v[70:71]
	global_load_dwordx4 v[70:73], v[74:75], off
	global_load_dwordx4 v[164:167], v[74:75], off offset:64
	global_load_dwordx4 v[168:171], v[74:75], off offset:512
	global_load_dwordx4 v[172:175], v[74:75], off offset:576
	s_waitcnt vmcnt(3)
	v_pk_add_f32 v[72:73], v[72:73], 1.0 op_sel_hi:[1,0]
	v_pk_add_f32 v[70:71], v[70:71], 1.0 op_sel_hi:[1,0]
	v_pk_mul_f32 v[72:73], v[142:143], v[72:73]
	v_pk_mul_f32 v[70:71], v[140:141], v[70:71]
	global_store_dwordx4 v[84:85], v[70:73], off
	s_waitcnt vmcnt(3)
	v_pk_add_f32 v[166:167], v[166:167], 1.0 op_sel_hi:[1,0]
	v_pk_add_f32 v[164:165], v[164:165], 1.0 op_sel_hi:[1,0]
	v_pk_mul_f32 v[166:167], v[138:139], v[166:167]
	v_pk_mul_f32 v[164:165], v[136:137], v[164:165]
	global_store_dwordx4 v[84:85], v[164:167], off offset:64
	s_waitcnt vmcnt(3)
	v_pk_add_f32 v[170:171], v[170:171], 1.0 op_sel_hi:[1,0]
	v_pk_add_f32 v[168:169], v[168:169], 1.0 op_sel_hi:[1,0]
	v_pk_mul_f32 v[170:171], v[134:135], v[170:171]
	v_pk_mul_f32 v[168:169], v[132:133], v[168:169]
	global_store_dwordx4 v[84:85], v[168:171], off offset:512
	s_waitcnt vmcnt(3)
	v_pk_add_f32 v[174:175], v[174:175], 1.0 op_sel_hi:[1,0]
	v_pk_add_f32 v[172:173], v[172:173], 1.0 op_sel_hi:[1,0]
	v_pk_mul_f32 v[174:175], v[130:131], v[174:175]
	v_pk_mul_f32 v[172:173], v[128:129], v[172:173]
	global_store_dwordx4 v[84:85], v[172:175], off offset:576
	s_nop 1
	v_add_u32_e32 v70, s17, v223
	v_ashrrev_i32_e32 v69, 2, v70
	v_or_b32_e32 v69, 8, v69
	v_mad_i64_i32 v[72:73], s[26:27], v69, s33, v[66:67]
	v_ashrrev_i32_e32 v71, 31, v70
	v_lshl_add_u64 v[74:75], v[72:73], 0, v[160:161]
	v_lshlrev_b64 v[70:71], 12, v[70:71]
	v_lshl_add_u64 v[84:85], v[64:65], 0, v[70:71]
	global_load_dwordx4 v[70:73], v[74:75], off
	global_load_dwordx4 v[164:167], v[74:75], off offset:64
	global_load_dwordx4 v[168:171], v[74:75], off offset:512
	global_load_dwordx4 v[172:175], v[74:75], off offset:576
	s_waitcnt vmcnt(3)
	v_pk_add_f32 v[72:73], v[72:73], 1.0 op_sel_hi:[1,0]
	v_pk_add_f32 v[70:71], v[70:71], 1.0 op_sel_hi:[1,0]
	v_pk_mul_f32 v[72:73], v[126:127], v[72:73]
	v_pk_mul_f32 v[70:71], v[124:125], v[70:71]
	global_store_dwordx4 v[84:85], v[70:73], off
	s_waitcnt vmcnt(3)
	v_pk_add_f32 v[166:167], v[166:167], 1.0 op_sel_hi:[1,0]
	v_pk_add_f32 v[164:165], v[164:165], 1.0 op_sel_hi:[1,0]
	v_pk_mul_f32 v[166:167], v[122:123], v[166:167]
	v_pk_mul_f32 v[164:165], v[120:121], v[164:165]
	global_store_dwordx4 v[84:85], v[164:167], off offset:64
	s_waitcnt vmcnt(3)
	v_pk_add_f32 v[170:171], v[170:171], 1.0 op_sel_hi:[1,0]
	v_pk_add_f32 v[168:169], v[168:169], 1.0 op_sel_hi:[1,0]
	v_pk_mul_f32 v[170:171], v[118:119], v[170:171]
	v_pk_mul_f32 v[168:169], v[116:117], v[168:169]
	global_store_dwordx4 v[84:85], v[168:171], off offset:512
	s_waitcnt vmcnt(3)
	v_pk_add_f32 v[174:175], v[174:175], 1.0 op_sel_hi:[1,0]
	v_pk_add_f32 v[172:173], v[172:173], 1.0 op_sel_hi:[1,0]
	v_pk_mul_f32 v[174:175], v[114:115], v[174:175]
	v_pk_mul_f32 v[172:173], v[112:113], v[172:173]
	global_store_dwordx4 v[84:85], v[172:175], off offset:576
	s_nop 1
	v_add_u32_e32 v70, s17, v224
	v_ashrrev_i32_e32 v69, 2, v70
	v_add_u32_e32 v69, 8, v69
	v_mad_i64_i32 v[72:73], s[26:27], v69, s33, v[66:67]
	v_ashrrev_i32_e32 v71, 31, v70
	v_lshl_add_u64 v[74:75], v[72:73], 0, v[160:161]
	v_lshlrev_b64 v[70:71], 12, v[70:71]
	v_lshl_add_u64 v[84:85], v[64:65], 0, v[70:71]
	global_load_dwordx4 v[70:73], v[74:75], off
	global_load_dwordx4 v[164:167], v[74:75], off offset:64
	global_load_dwordx4 v[168:171], v[74:75], off offset:512
	global_load_dwordx4 v[172:175], v[74:75], off offset:576
	s_waitcnt vmcnt(3)
	v_pk_add_f32 v[72:73], v[72:73], 1.0 op_sel_hi:[1,0]
	v_pk_add_f32 v[70:71], v[70:71], 1.0 op_sel_hi:[1,0]
	v_pk_mul_f32 v[72:73], v[110:111], v[72:73]
	v_pk_mul_f32 v[70:71], v[108:109], v[70:71]
	global_store_dwordx4 v[84:85], v[70:73], off
	s_waitcnt vmcnt(3)
	v_pk_add_f32 v[166:167], v[166:167], 1.0 op_sel_hi:[1,0]
	v_pk_add_f32 v[164:165], v[164:165], 1.0 op_sel_hi:[1,0]
	v_pk_mul_f32 v[166:167], v[106:107], v[166:167]
	v_pk_mul_f32 v[164:165], v[104:105], v[164:165]
	global_store_dwordx4 v[84:85], v[164:167], off offset:64
	s_waitcnt vmcnt(3)
	v_pk_add_f32 v[170:171], v[170:171], 1.0 op_sel_hi:[1,0]
	v_pk_add_f32 v[168:169], v[168:169], 1.0 op_sel_hi:[1,0]
	v_pk_mul_f32 v[170:171], v[102:103], v[170:171]
	v_pk_mul_f32 v[168:169], v[100:101], v[168:169]
	global_store_dwordx4 v[84:85], v[168:171], off offset:512
	s_waitcnt vmcnt(3)
	v_pk_add_f32 v[174:175], v[174:175], 1.0 op_sel_hi:[1,0]
	v_pk_add_f32 v[172:173], v[172:173], 1.0 op_sel_hi:[1,0]
	v_pk_mul_f32 v[174:175], v[98:99], v[174:175]
	v_pk_mul_f32 v[172:173], v[96:97], v[172:173]
	global_store_dwordx4 v[84:85], v[172:175], off offset:576
	s_nop 1
	v_add_u32_e32 v70, s17, v225
	v_ashrrev_i32_e32 v69, 2, v70
	v_add_u32_e32 v69, 8, v69
	v_mad_i64_i32 v[72:73], s[26:27], v69, s33, v[66:67]
	v_ashrrev_i32_e32 v71, 31, v70
	v_lshl_add_u64 v[74:75], v[72:73], 0, v[160:161]
	v_lshlrev_b64 v[70:71], 12, v[70:71]
	v_lshl_add_u64 v[84:85], v[64:65], 0, v[70:71]
	global_load_dwordx4 v[70:73], v[74:75], off
	global_load_dwordx4 v[164:167], v[74:75], off offset:64
	global_load_dwordx4 v[168:171], v[74:75], off offset:512
	global_load_dwordx4 v[172:175], v[74:75], off offset:576
	s_waitcnt vmcnt(3)
	v_pk_add_f32 v[72:73], v[72:73], 1.0 op_sel_hi:[1,0]
	v_pk_add_f32 v[70:71], v[70:71], 1.0 op_sel_hi:[1,0]
	v_pk_mul_f32 v[72:73], v[94:95], v[72:73]
	v_pk_mul_f32 v[70:71], v[92:93], v[70:71]
	global_store_dwordx4 v[84:85], v[70:73], off
	s_waitcnt vmcnt(3)
	v_pk_add_f32 v[166:167], v[166:167], 1.0 op_sel_hi:[1,0]
	v_pk_add_f32 v[164:165], v[164:165], 1.0 op_sel_hi:[1,0]
	v_pk_mul_f32 v[166:167], v[90:91], v[166:167]
	v_pk_mul_f32 v[164:165], v[88:89], v[164:165]
	global_store_dwordx4 v[84:85], v[164:167], off offset:64
	s_waitcnt vmcnt(3)
	v_pk_add_f32 v[170:171], v[170:171], 1.0 op_sel_hi:[1,0]
	v_pk_add_f32 v[168:169], v[168:169], 1.0 op_sel_hi:[1,0]
	v_pk_mul_f32 v[170:171], v[82:83], v[170:171]
	v_pk_mul_f32 v[168:169], v[80:81], v[168:169]
	global_store_dwordx4 v[84:85], v[168:171], off offset:512
	s_waitcnt vmcnt(3)
	v_pk_add_f32 v[174:175], v[174:175], 1.0 op_sel_hi:[1,0]
	v_pk_add_f32 v[172:173], v[172:173], 1.0 op_sel_hi:[1,0]
	v_pk_mul_f32 v[174:175], v[78:79], v[174:175]
	v_pk_mul_f32 v[172:173], v[76:77], v[172:173]
	global_store_dwordx4 v[84:85], v[172:175], off offset:576
	s_nop 1
	v_add_u32_e32 v70, 0x80, v68
	v_ashrrev_i32_e32 v69, 2, v70
	v_or_b32_e32 v69, 8, v69
	v_mad_i64_i32 v[72:73], s[26:27], v69, s33, v[66:67]
	v_ashrrev_i32_e32 v71, 31, v70
	v_lshl_add_u64 v[74:75], v[72:73], 0, v[160:161]
	v_lshlrev_b64 v[70:71], 12, v[70:71]
	v_lshl_add_u64 v[84:85], v[64:65], 0, v[70:71]
	global_load_dwordx4 v[70:73], v[74:75], off
	global_load_dwordx4 v[164:167], v[74:75], off offset:64
	global_load_dwordx4 v[168:171], v[74:75], off offset:512
	global_load_dwordx4 v[172:175], v[74:75], off offset:576
	s_waitcnt vmcnt(3)
	v_pk_add_f32 v[72:73], v[72:73], 1.0 op_sel_hi:[1,0]
	v_pk_add_f32 v[70:71], v[70:71], 1.0 op_sel_hi:[1,0]
	v_pk_mul_f32 v[72:73], v[62:63], v[72:73]
	v_pk_mul_f32 v[70:71], v[60:61], v[70:71]
	global_store_dwordx4 v[84:85], v[70:73], off
	s_waitcnt vmcnt(3)
	v_pk_add_f32 v[166:167], v[166:167], 1.0 op_sel_hi:[1,0]
	v_pk_add_f32 v[164:165], v[164:165], 1.0 op_sel_hi:[1,0]
	v_pk_mul_f32 v[166:167], v[58:59], v[166:167]
	v_pk_mul_f32 v[164:165], v[56:57], v[164:165]
	global_store_dwordx4 v[84:85], v[164:167], off offset:64
	s_waitcnt vmcnt(3)
	v_pk_add_f32 v[170:171], v[170:171], 1.0 op_sel_hi:[1,0]
	v_pk_add_f32 v[168:169], v[168:169], 1.0 op_sel_hi:[1,0]
	v_pk_mul_f32 v[170:171], v[54:55], v[170:171]
	v_pk_mul_f32 v[168:169], v[52:53], v[168:169]
	global_store_dwordx4 v[84:85], v[168:171], off offset:512
	s_waitcnt vmcnt(3)
	v_pk_add_f32 v[174:175], v[174:175], 1.0 op_sel_hi:[1,0]
	v_pk_add_f32 v[172:173], v[172:173], 1.0 op_sel_hi:[1,0]
	v_pk_mul_f32 v[174:175], v[50:51], v[174:175]
	v_pk_mul_f32 v[172:173], v[48:49], v[172:173]
	global_store_dwordx4 v[84:85], v[172:175], off offset:576
	s_nop 1
	v_add_u32_e32 v70, 0x90, v68
	v_ashrrev_i32_e32 v69, 2, v70
	v_or_b32_e32 v69, 8, v69
	v_mad_i64_i32 v[72:73], s[26:27], v69, s33, v[66:67]
	v_ashrrev_i32_e32 v71, 31, v70
	v_lshl_add_u64 v[74:75], v[72:73], 0, v[160:161]
	v_lshlrev_b64 v[70:71], 12, v[70:71]
	v_lshl_add_u64 v[84:85], v[64:65], 0, v[70:71]
	global_load_dwordx4 v[70:73], v[74:75], off
	global_load_dwordx4 v[164:167], v[74:75], off offset:64
	global_load_dwordx4 v[168:171], v[74:75], off offset:512
	global_load_dwordx4 v[172:175], v[74:75], off offset:576
	s_waitcnt vmcnt(3)
	v_pk_add_f32 v[72:73], v[72:73], 1.0 op_sel_hi:[1,0]
	v_pk_add_f32 v[70:71], v[70:71], 1.0 op_sel_hi:[1,0]
	v_pk_mul_f32 v[72:73], v[46:47], v[72:73]
	v_pk_mul_f32 v[70:71], v[44:45], v[70:71]
	global_store_dwordx4 v[84:85], v[70:73], off
	s_waitcnt vmcnt(3)
	v_pk_add_f32 v[166:167], v[166:167], 1.0 op_sel_hi:[1,0]
	v_pk_add_f32 v[164:165], v[164:165], 1.0 op_sel_hi:[1,0]
	v_pk_mul_f32 v[166:167], v[42:43], v[166:167]
	v_pk_mul_f32 v[164:165], v[40:41], v[164:165]
	global_store_dwordx4 v[84:85], v[164:167], off offset:64
	s_waitcnt vmcnt(3)
	v_pk_add_f32 v[170:171], v[170:171], 1.0 op_sel_hi:[1,0]
	v_pk_add_f32 v[168:169], v[168:169], 1.0 op_sel_hi:[1,0]
	v_pk_mul_f32 v[170:171], v[38:39], v[170:171]
	v_pk_mul_f32 v[168:169], v[36:37], v[168:169]
	global_store_dwordx4 v[84:85], v[168:171], off offset:512
	s_waitcnt vmcnt(3)
	v_pk_add_f32 v[174:175], v[174:175], 1.0 op_sel_hi:[1,0]
	v_pk_add_f32 v[172:173], v[172:173], 1.0 op_sel_hi:[1,0]
	v_pk_mul_f32 v[174:175], v[34:35], v[174:175]
	v_pk_mul_f32 v[172:173], v[32:33], v[172:173]
	global_store_dwordx4 v[84:85], v[172:175], off offset:576
	s_nop 1
	v_add_u32_e32 v70, 0xa0, v68
	v_ashrrev_i32_e32 v69, 2, v70
	v_add_u32_e32 v69, 8, v69
	v_mad_i64_i32 v[72:73], s[26:27], v69, s33, v[66:67]
	v_ashrrev_i32_e32 v71, 31, v70
	v_lshl_add_u64 v[74:75], v[72:73], 0, v[160:161]
	v_lshlrev_b64 v[70:71], 12, v[70:71]
	v_lshl_add_u64 v[84:85], v[64:65], 0, v[70:71]
	global_load_dwordx4 v[70:73], v[74:75], off
	global_load_dwordx4 v[164:167], v[74:75], off offset:64
	global_load_dwordx4 v[168:171], v[74:75], off offset:512
	global_load_dwordx4 v[172:175], v[74:75], off offset:576
	v_add_u32_e32 v68, 0xb0, v68
	v_ashrrev_i32_e32 v69, 2, v68
	v_add_u32_e32 v69, 8, v69
	v_mad_i64_i32 v[66:67], s[26:27], v69, s33, v[66:67]
	v_ashrrev_i32_e32 v69, 31, v68
	s_waitcnt vmcnt(3)
	v_pk_add_f32 v[72:73], v[72:73], 1.0 op_sel_hi:[1,0]
	v_pk_add_f32 v[70:71], v[70:71], 1.0 op_sel_hi:[1,0]
	v_pk_mul_f32 v[72:73], v[30:31], v[72:73]
	v_pk_mul_f32 v[70:71], v[28:29], v[70:71]
	global_store_dwordx4 v[84:85], v[70:73], off
	s_waitcnt vmcnt(3)
	v_pk_add_f32 v[166:167], v[166:167], 1.0 op_sel_hi:[1,0]
	v_pk_add_f32 v[164:165], v[164:165], 1.0 op_sel_hi:[1,0]
	v_pk_mul_f32 v[166:167], v[26:27], v[166:167]
	v_pk_mul_f32 v[164:165], v[24:25], v[164:165]
	global_store_dwordx4 v[84:85], v[164:167], off offset:64
	s_waitcnt vmcnt(3)
	v_pk_add_f32 v[170:171], v[170:171], 1.0 op_sel_hi:[1,0]
	v_pk_add_f32 v[168:169], v[168:169], 1.0 op_sel_hi:[1,0]
	v_pk_mul_f32 v[170:171], v[22:23], v[170:171]
	v_pk_mul_f32 v[168:169], v[20:21], v[168:169]
	global_store_dwordx4 v[84:85], v[168:171], off offset:512
	s_waitcnt vmcnt(3)
	v_pk_add_f32 v[174:175], v[174:175], 1.0 op_sel_hi:[1,0]
	v_pk_add_f32 v[172:173], v[172:173], 1.0 op_sel_hi:[1,0]
	v_pk_mul_f32 v[174:175], v[18:19], v[174:175]
	v_pk_mul_f32 v[172:173], v[16:17], v[172:173]
	global_store_dwordx4 v[84:85], v[172:175], off offset:576
	s_nop 1
	v_lshl_add_u64 v[70:71], v[66:67], 0, v[160:161]
	v_lshlrev_b64 v[66:67], 12, v[68:69]
	v_lshl_add_u64 v[68:69], v[64:65], 0, v[66:67]
	global_load_dwordx4 v[64:67], v[70:71], off
	global_load_dwordx4 v[164:167], v[70:71], off offset:64
	global_load_dwordx4 v[168:171], v[70:71], off offset:512
	global_load_dwordx4 v[172:175], v[70:71], off offset:576
	s_waitcnt vmcnt(3)
	v_pk_add_f32 v[66:67], v[66:67], 1.0 op_sel_hi:[1,0]
	v_pk_add_f32 v[64:65], v[64:65], 1.0 op_sel_hi:[1,0]
	v_pk_mul_f32 v[66:67], v[14:15], v[66:67]
	v_pk_mul_f32 v[64:65], v[12:13], v[64:65]
	global_store_dwordx4 v[68:69], v[64:67], off
	s_waitcnt vmcnt(3)
	v_pk_add_f32 v[166:167], v[166:167], 1.0 op_sel_hi:[1,0]
	v_pk_add_f32 v[164:165], v[164:165], 1.0 op_sel_hi:[1,0]
	v_pk_mul_f32 v[166:167], v[10:11], v[166:167]
	v_pk_mul_f32 v[164:165], v[8:9], v[164:165]
	global_store_dwordx4 v[68:69], v[164:167], off offset:64
	s_waitcnt vmcnt(3)
	v_pk_add_f32 v[170:171], v[170:171], 1.0 op_sel_hi:[1,0]
	v_pk_add_f32 v[168:169], v[168:169], 1.0 op_sel_hi:[1,0]
	v_pk_mul_f32 v[170:171], v[6:7], v[170:171]
	v_pk_mul_f32 v[168:169], v[4:5], v[168:169]
	global_store_dwordx4 v[68:69], v[168:171], off offset:512
	s_waitcnt vmcnt(3)
	v_pk_add_f32 v[174:175], v[174:175], 1.0 op_sel_hi:[1,0]
	v_pk_add_f32 v[172:173], v[172:173], 1.0 op_sel_hi:[1,0]
	v_pk_mul_f32 v[174:175], v[2:3], v[174:175]
	v_pk_mul_f32 v[172:173], v[0:1], v[172:173]
	global_store_dwordx4 v[68:69], v[172:175], off offset:576
	s_cbranch_execnz .LBB0_1161

.LBB0_1377:
	s_ashr_i32 s25, s77, 31
	s_lshr_b32 s25, s25, 30
	s_add_i32 s25, s77, s25
	s_ashr_i32 s34, s25, 2
	s_ashr_i32 s35, s34, 31
	s_lshl_b64 s[34:35], s[34:35], 21
	s_add_u32 s34, s59, s34
	s_addc_u32 s35, s70, s35
	s_lshl_b32 s25, s76, 8
	v_add_u32_e32 v132, s25, v222
	v_ashrrev_i32_e32 v130, 2, v132
	v_or_b32_e32 v133, 8, v130
	v_mov_b64_e32 v[130:131], s[12:13]
	v_lshl_add_u64 v[128:129], s[34:35], 0, v[160:161]
	v_mad_i64_i32 v[134:135], s[34:35], v133, s33, v[130:131]
	v_ashrrev_i32_e32 v133, 31, v132
	v_lshl_add_u64 v[138:139], v[134:135], 0, v[160:161]
	v_lshlrev_b64 v[134:135], 12, v[132:133]
	v_lshl_add_u64 v[140:141], v[128:129], 0, v[134:135]
	global_load_dwordx4 v[134:137], v[138:139], off
	global_load_dwordx4 v[164:167], v[138:139], off offset:64
	global_load_dwordx4 v[168:171], v[138:139], off offset:512
	global_load_dwordx4 v[172:175], v[138:139], off offset:576
	s_waitcnt vmcnt(3)
	v_pk_fma_f32 v[136:137], v[136:137], 0.5, 0.5 op_sel_hi:[1,0,0]
	v_pk_fma_f32 v[134:135], v[134:135], 0.5, 0.5 op_sel_hi:[1,0,0]
	v_pk_mul_f32 v[136:137], v[126:127], v[136:137]
	v_pk_mul_f32 v[134:135], v[124:125], v[134:135]
	global_store_dwordx4 v[140:141], v[134:137], off
	s_waitcnt vmcnt(3)
	v_pk_fma_f32 v[166:167], v[166:167], 0.5, 0.5 op_sel_hi:[1,0,0]
	v_pk_fma_f32 v[164:165], v[164:165], 0.5, 0.5 op_sel_hi:[1,0,0]
	v_pk_mul_f32 v[166:167], v[122:123], v[166:167]
	v_pk_mul_f32 v[164:165], v[120:121], v[164:165]
	global_store_dwordx4 v[140:141], v[164:167], off offset:64
	s_waitcnt vmcnt(3)
	v_pk_fma_f32 v[170:171], v[170:171], 0.5, 0.5 op_sel_hi:[1,0,0]
	v_pk_fma_f32 v[168:169], v[168:169], 0.5, 0.5 op_sel_hi:[1,0,0]
	v_pk_mul_f32 v[170:171], v[118:119], v[170:171]
	v_pk_mul_f32 v[168:169], v[116:117], v[168:169]
	global_store_dwordx4 v[140:141], v[168:171], off offset:512
	s_waitcnt vmcnt(3)
	v_pk_fma_f32 v[174:175], v[174:175], 0.5, 0.5 op_sel_hi:[1,0,0]
	v_pk_fma_f32 v[172:173], v[172:173], 0.5, 0.5 op_sel_hi:[1,0,0]
	v_pk_mul_f32 v[174:175], v[114:115], v[174:175]
	v_pk_mul_f32 v[172:173], v[112:113], v[172:173]
	global_store_dwordx4 v[140:141], v[172:175], off offset:576
	s_nop 1
	v_add_u32_e32 v134, s25, v223
	v_ashrrev_i32_e32 v133, 2, v134
	v_or_b32_e32 v133, 8, v133
	v_mad_i64_i32 v[136:137], s[34:35], v133, s33, v[130:131]
	v_ashrrev_i32_e32 v135, 31, v134
	v_lshl_add_u64 v[138:139], v[136:137], 0, v[160:161]
	v_lshlrev_b64 v[134:135], 12, v[134:135]
	v_lshl_add_u64 v[140:141], v[128:129], 0, v[134:135]
	global_load_dwordx4 v[134:137], v[138:139], off
	global_load_dwordx4 v[164:167], v[138:139], off offset:64
	global_load_dwordx4 v[168:171], v[138:139], off offset:512
	global_load_dwordx4 v[172:175], v[138:139], off offset:576
	s_waitcnt vmcnt(3)
	v_pk_fma_f32 v[136:137], v[136:137], 0.5, 0.5 op_sel_hi:[1,0,0]
	v_pk_fma_f32 v[134:135], v[134:135], 0.5, 0.5 op_sel_hi:[1,0,0]
	v_pk_mul_f32 v[136:137], v[110:111], v[136:137]
	v_pk_mul_f32 v[134:135], v[108:109], v[134:135]
	global_store_dwordx4 v[140:141], v[134:137], off
	s_waitcnt vmcnt(3)
	v_pk_fma_f32 v[166:167], v[166:167], 0.5, 0.5 op_sel_hi:[1,0,0]
	v_pk_fma_f32 v[164:165], v[164:165], 0.5, 0.5 op_sel_hi:[1,0,0]
	v_pk_mul_f32 v[166:167], v[106:107], v[166:167]
	v_pk_mul_f32 v[164:165], v[104:105], v[164:165]
	global_store_dwordx4 v[140:141], v[164:167], off offset:64
	s_waitcnt vmcnt(3)
	v_pk_fma_f32 v[170:171], v[170:171], 0.5, 0.5 op_sel_hi:[1,0,0]
	v_pk_fma_f32 v[168:169], v[168:169], 0.5, 0.5 op_sel_hi:[1,0,0]
	v_pk_mul_f32 v[170:171], v[102:103], v[170:171]
	v_pk_mul_f32 v[168:169], v[100:101], v[168:169]
	global_store_dwordx4 v[140:141], v[168:171], off offset:512
	s_waitcnt vmcnt(3)
	v_pk_fma_f32 v[174:175], v[174:175], 0.5, 0.5 op_sel_hi:[1,0,0]
	v_pk_fma_f32 v[172:173], v[172:173], 0.5, 0.5 op_sel_hi:[1,0,0]
	v_pk_mul_f32 v[174:175], v[98:99], v[174:175]
	v_pk_mul_f32 v[172:173], v[96:97], v[172:173]
	global_store_dwordx4 v[140:141], v[172:175], off offset:576
	s_nop 1
	v_add_u32_e32 v134, s25, v224
	v_ashrrev_i32_e32 v133, 2, v134
	v_add_u32_e32 v133, 8, v133
	v_mad_i64_i32 v[136:137], s[34:35], v133, s33, v[130:131]
	v_ashrrev_i32_e32 v135, 31, v134
	v_lshl_add_u64 v[138:139], v[136:137], 0, v[160:161]
	v_lshlrev_b64 v[134:135], 12, v[134:135]
	v_lshl_add_u64 v[140:141], v[128:129], 0, v[134:135]
	global_load_dwordx4 v[134:137], v[138:139], off
	global_load_dwordx4 v[164:167], v[138:139], off offset:64
	global_load_dwordx4 v[168:171], v[138:139], off offset:512
	global_load_dwordx4 v[172:175], v[138:139], off offset:576
	s_waitcnt vmcnt(3)
	v_pk_fma_f32 v[136:137], v[136:137], 0.5, 0.5 op_sel_hi:[1,0,0]
	v_pk_fma_f32 v[134:135], v[134:135], 0.5, 0.5 op_sel_hi:[1,0,0]
	v_pk_mul_f32 v[136:137], v[94:95], v[136:137]
	v_pk_mul_f32 v[134:135], v[92:93], v[134:135]
	global_store_dwordx4 v[140:141], v[134:137], off
	s_waitcnt vmcnt(3)
	v_pk_fma_f32 v[166:167], v[166:167], 0.5, 0.5 op_sel_hi:[1,0,0]
	v_pk_fma_f32 v[164:165], v[164:165], 0.5, 0.5 op_sel_hi:[1,0,0]
	v_pk_mul_f32 v[166:167], v[90:91], v[166:167]
	v_pk_mul_f32 v[164:165], v[88:89], v[164:165]
	global_store_dwordx4 v[140:141], v[164:167], off offset:64
	s_waitcnt vmcnt(3)
	v_pk_fma_f32 v[170:171], v[170:171], 0.5, 0.5 op_sel_hi:[1,0,0]
	v_pk_fma_f32 v[168:169], v[168:169], 0.5, 0.5 op_sel_hi:[1,0,0]
	v_pk_mul_f32 v[170:171], v[86:87], v[170:171]
	v_pk_mul_f32 v[168:169], v[84:85], v[168:169]
	global_store_dwordx4 v[140:141], v[168:171], off offset:512
	s_waitcnt vmcnt(3)
	v_pk_fma_f32 v[174:175], v[174:175], 0.5, 0.5 op_sel_hi:[1,0,0]
	v_pk_fma_f32 v[172:173], v[172:173], 0.5, 0.5 op_sel_hi:[1,0,0]
	v_pk_mul_f32 v[174:175], v[82:83], v[174:175]
	v_pk_mul_f32 v[172:173], v[80:81], v[172:173]
	global_store_dwordx4 v[140:141], v[172:175], off offset:576
	s_nop 1
	v_add_u32_e32 v134, s25, v225
	v_ashrrev_i32_e32 v133, 2, v134
	v_add_u32_e32 v133, 8, v133
	v_mad_i64_i32 v[136:137], s[34:35], v133, s33, v[130:131]
	v_ashrrev_i32_e32 v135, 31, v134
	v_lshl_add_u64 v[138:139], v[136:137], 0, v[160:161]
	v_lshlrev_b64 v[134:135], 12, v[134:135]
	v_lshl_add_u64 v[140:141], v[128:129], 0, v[134:135]
	global_load_dwordx4 v[134:137], v[138:139], off
	global_load_dwordx4 v[164:167], v[138:139], off offset:64
	global_load_dwordx4 v[168:171], v[138:139], off offset:512
	global_load_dwordx4 v[172:175], v[138:139], off offset:576
	s_waitcnt vmcnt(3)
	v_pk_fma_f32 v[136:137], v[136:137], 0.5, 0.5 op_sel_hi:[1,0,0]
	v_pk_fma_f32 v[134:135], v[134:135], 0.5, 0.5 op_sel_hi:[1,0,0]
	v_pk_mul_f32 v[136:137], v[78:79], v[136:137]
	v_pk_mul_f32 v[134:135], v[76:77], v[134:135]
	global_store_dwordx4 v[140:141], v[134:137], off
	s_waitcnt vmcnt(3)
	v_pk_fma_f32 v[166:167], v[166:167], 0.5, 0.5 op_sel_hi:[1,0,0]
	v_pk_fma_f32 v[164:165], v[164:165], 0.5, 0.5 op_sel_hi:[1,0,0]
	v_pk_mul_f32 v[166:167], v[74:75], v[166:167]
	v_pk_mul_f32 v[164:165], v[72:73], v[164:165]
	global_store_dwordx4 v[140:141], v[164:167], off offset:64
	s_waitcnt vmcnt(3)
	v_pk_fma_f32 v[170:171], v[170:171], 0.5, 0.5 op_sel_hi:[1,0,0]
	v_pk_fma_f32 v[168:169], v[168:169], 0.5, 0.5 op_sel_hi:[1,0,0]
	v_pk_mul_f32 v[170:171], v[70:71], v[170:171]
	v_pk_mul_f32 v[168:169], v[68:69], v[168:169]
	global_store_dwordx4 v[140:141], v[168:171], off offset:512
	s_waitcnt vmcnt(3)
	v_pk_fma_f32 v[174:175], v[174:175], 0.5, 0.5 op_sel_hi:[1,0,0]
	v_pk_fma_f32 v[172:173], v[172:173], 0.5, 0.5 op_sel_hi:[1,0,0]
	v_pk_mul_f32 v[174:175], v[66:67], v[174:175]
	v_pk_mul_f32 v[172:173], v[64:65], v[172:173]
	global_store_dwordx4 v[140:141], v[172:175], off offset:576
	s_nop 1
	v_add_u32_e32 v134, 0x80, v132
	v_ashrrev_i32_e32 v133, 2, v134
	v_or_b32_e32 v133, 8, v133
	v_mad_i64_i32 v[136:137], s[34:35], v133, s33, v[130:131]
	v_ashrrev_i32_e32 v135, 31, v134
	v_lshl_add_u64 v[138:139], v[136:137], 0, v[160:161]
	v_lshlrev_b64 v[134:135], 12, v[134:135]
	v_lshl_add_u64 v[140:141], v[128:129], 0, v[134:135]
	global_load_dwordx4 v[134:137], v[138:139], off
	global_load_dwordx4 v[164:167], v[138:139], off offset:64
	global_load_dwordx4 v[168:171], v[138:139], off offset:512
	global_load_dwordx4 v[172:175], v[138:139], off offset:576
	s_waitcnt vmcnt(3)
	v_pk_fma_f32 v[136:137], v[136:137], 0.5, 0.5 op_sel_hi:[1,0,0]
	v_pk_fma_f32 v[134:135], v[134:135], 0.5, 0.5 op_sel_hi:[1,0,0]
	v_pk_mul_f32 v[136:137], v[62:63], v[136:137]
	v_pk_mul_f32 v[134:135], v[60:61], v[134:135]
	global_store_dwordx4 v[140:141], v[134:137], off
	s_waitcnt vmcnt(3)
	v_pk_fma_f32 v[166:167], v[166:167], 0.5, 0.5 op_sel_hi:[1,0,0]
	v_pk_fma_f32 v[164:165], v[164:165], 0.5, 0.5 op_sel_hi:[1,0,0]
	v_pk_mul_f32 v[166:167], v[58:59], v[166:167]
	v_pk_mul_f32 v[164:165], v[56:57], v[164:165]
	global_store_dwordx4 v[140:141], v[164:167], off offset:64
	s_waitcnt vmcnt(3)
	v_pk_fma_f32 v[170:171], v[170:171], 0.5, 0.5 op_sel_hi:[1,0,0]
	v_pk_fma_f32 v[168:169], v[168:169], 0.5, 0.5 op_sel_hi:[1,0,0]
	v_pk_mul_f32 v[170:171], v[54:55], v[170:171]
	v_pk_mul_f32 v[168:169], v[52:53], v[168:169]
	global_store_dwordx4 v[140:141], v[168:171], off offset:512
	s_waitcnt vmcnt(3)
	v_pk_fma_f32 v[174:175], v[174:175], 0.5, 0.5 op_sel_hi:[1,0,0]
	v_pk_fma_f32 v[172:173], v[172:173], 0.5, 0.5 op_sel_hi:[1,0,0]
	v_pk_mul_f32 v[174:175], v[50:51], v[174:175]
	v_pk_mul_f32 v[172:173], v[48:49], v[172:173]
	global_store_dwordx4 v[140:141], v[172:175], off offset:576
	s_nop 1
	v_add_u32_e32 v134, 0x90, v132
	v_ashrrev_i32_e32 v133, 2, v134
	v_or_b32_e32 v133, 8, v133
	v_mad_i64_i32 v[136:137], s[34:35], v133, s33, v[130:131]
	v_ashrrev_i32_e32 v135, 31, v134
	v_lshl_add_u64 v[138:139], v[136:137], 0, v[160:161]
	v_lshlrev_b64 v[134:135], 12, v[134:135]
	v_lshl_add_u64 v[140:141], v[128:129], 0, v[134:135]
	global_load_dwordx4 v[134:137], v[138:139], off
	global_load_dwordx4 v[164:167], v[138:139], off offset:64
	global_load_dwordx4 v[168:171], v[138:139], off offset:512
	global_load_dwordx4 v[172:175], v[138:139], off offset:576
	s_waitcnt vmcnt(3)
	v_pk_fma_f32 v[136:137], v[136:137], 0.5, 0.5 op_sel_hi:[1,0,0]
	v_pk_fma_f32 v[134:135], v[134:135], 0.5, 0.5 op_sel_hi:[1,0,0]
	v_pk_mul_f32 v[136:137], v[46:47], v[136:137]
	v_pk_mul_f32 v[134:135], v[44:45], v[134:135]
	global_store_dwordx4 v[140:141], v[134:137], off
	s_waitcnt vmcnt(3)
	v_pk_fma_f32 v[166:167], v[166:167], 0.5, 0.5 op_sel_hi:[1,0,0]
	v_pk_fma_f32 v[164:165], v[164:165], 0.5, 0.5 op_sel_hi:[1,0,0]
	v_pk_mul_f32 v[166:167], v[42:43], v[166:167]
	v_pk_mul_f32 v[164:165], v[40:41], v[164:165]
	global_store_dwordx4 v[140:141], v[164:167], off offset:64
	s_waitcnt vmcnt(3)
	v_pk_fma_f32 v[170:171], v[170:171], 0.5, 0.5 op_sel_hi:[1,0,0]
	v_pk_fma_f32 v[168:169], v[168:169], 0.5, 0.5 op_sel_hi:[1,0,0]
	v_pk_mul_f32 v[170:171], v[38:39], v[170:171]
	v_pk_mul_f32 v[168:169], v[36:37], v[168:169]
	global_store_dwordx4 v[140:141], v[168:171], off offset:512
	s_waitcnt vmcnt(3)
	v_pk_fma_f32 v[174:175], v[174:175], 0.5, 0.5 op_sel_hi:[1,0,0]
	v_pk_fma_f32 v[172:173], v[172:173], 0.5, 0.5 op_sel_hi:[1,0,0]
	v_pk_mul_f32 v[174:175], v[34:35], v[174:175]
	v_pk_mul_f32 v[172:173], v[32:33], v[172:173]
	global_store_dwordx4 v[140:141], v[172:175], off offset:576
	s_nop 1
	v_add_u32_e32 v134, 0xa0, v132
	v_ashrrev_i32_e32 v133, 2, v134
	v_add_u32_e32 v133, 8, v133
	v_mad_i64_i32 v[136:137], s[34:35], v133, s33, v[130:131]
	v_ashrrev_i32_e32 v135, 31, v134
	v_lshl_add_u64 v[138:139], v[136:137], 0, v[160:161]
	v_lshlrev_b64 v[134:135], 12, v[134:135]
	v_lshl_add_u64 v[140:141], v[128:129], 0, v[134:135]
	global_load_dwordx4 v[134:137], v[138:139], off
	global_load_dwordx4 v[164:167], v[138:139], off offset:64
	global_load_dwordx4 v[168:171], v[138:139], off offset:512
	global_load_dwordx4 v[172:175], v[138:139], off offset:576
	v_add_u32_e32 v132, 0xb0, v132
	v_ashrrev_i32_e32 v133, 2, v132
	v_add_u32_e32 v133, 8, v133
	v_mad_i64_i32 v[130:131], s[34:35], v133, s33, v[130:131]
	v_ashrrev_i32_e32 v133, 31, v132
	s_waitcnt vmcnt(3)
	v_pk_fma_f32 v[136:137], v[136:137], 0.5, 0.5 op_sel_hi:[1,0,0]
	v_pk_fma_f32 v[134:135], v[134:135], 0.5, 0.5 op_sel_hi:[1,0,0]
	v_pk_mul_f32 v[136:137], v[30:31], v[136:137]
	v_pk_mul_f32 v[134:135], v[28:29], v[134:135]
	global_store_dwordx4 v[140:141], v[134:137], off
	s_waitcnt vmcnt(3)
	v_pk_fma_f32 v[166:167], v[166:167], 0.5, 0.5 op_sel_hi:[1,0,0]
	v_pk_fma_f32 v[164:165], v[164:165], 0.5, 0.5 op_sel_hi:[1,0,0]
	v_pk_mul_f32 v[166:167], v[26:27], v[166:167]
	v_pk_mul_f32 v[164:165], v[24:25], v[164:165]
	global_store_dwordx4 v[140:141], v[164:167], off offset:64
	s_waitcnt vmcnt(3)
	v_pk_fma_f32 v[170:171], v[170:171], 0.5, 0.5 op_sel_hi:[1,0,0]
	v_pk_fma_f32 v[168:169], v[168:169], 0.5, 0.5 op_sel_hi:[1,0,0]
	v_pk_mul_f32 v[170:171], v[22:23], v[170:171]
	v_pk_mul_f32 v[168:169], v[20:21], v[168:169]
	global_store_dwordx4 v[140:141], v[168:171], off offset:512
	s_waitcnt vmcnt(3)
	v_pk_fma_f32 v[174:175], v[174:175], 0.5, 0.5 op_sel_hi:[1,0,0]
	v_pk_fma_f32 v[172:173], v[172:173], 0.5, 0.5 op_sel_hi:[1,0,0]
	v_pk_mul_f32 v[174:175], v[18:19], v[174:175]
	v_pk_mul_f32 v[172:173], v[16:17], v[172:173]
	global_store_dwordx4 v[140:141], v[172:175], off offset:576
	s_nop 1
	v_lshl_add_u64 v[134:135], v[130:131], 0, v[160:161]
	v_lshlrev_b64 v[130:131], 12, v[132:133]
	v_lshl_add_u64 v[132:133], v[128:129], 0, v[130:131]
	global_load_dwordx4 v[128:131], v[134:135], off
	global_load_dwordx4 v[164:167], v[134:135], off offset:64
	global_load_dwordx4 v[168:171], v[134:135], off offset:512
	global_load_dwordx4 v[172:175], v[134:135], off offset:576
	s_waitcnt vmcnt(3)
	v_pk_fma_f32 v[130:131], v[130:131], 0.5, 0.5 op_sel_hi:[1,0,0]
	v_pk_fma_f32 v[128:129], v[128:129], 0.5, 0.5 op_sel_hi:[1,0,0]
	v_pk_mul_f32 v[130:131], v[14:15], v[130:131]
	v_pk_mul_f32 v[128:129], v[12:13], v[128:129]
	global_store_dwordx4 v[132:133], v[128:131], off
	s_waitcnt vmcnt(3)
	v_pk_fma_f32 v[166:167], v[166:167], 0.5, 0.5 op_sel_hi:[1,0,0]
	v_pk_fma_f32 v[164:165], v[164:165], 0.5, 0.5 op_sel_hi:[1,0,0]
	v_pk_mul_f32 v[166:167], v[10:11], v[166:167]
	v_pk_mul_f32 v[164:165], v[8:9], v[164:165]
	global_store_dwordx4 v[132:133], v[164:167], off offset:64
	s_waitcnt vmcnt(3)
	v_pk_fma_f32 v[170:171], v[170:171], 0.5, 0.5 op_sel_hi:[1,0,0]
	v_pk_fma_f32 v[168:169], v[168:169], 0.5, 0.5 op_sel_hi:[1,0,0]
	v_pk_mul_f32 v[170:171], v[6:7], v[170:171]
	v_pk_mul_f32 v[168:169], v[4:5], v[168:169]
	global_store_dwordx4 v[132:133], v[168:171], off offset:512
	s_waitcnt vmcnt(3)
	v_pk_fma_f32 v[174:175], v[174:175], 0.5, 0.5 op_sel_hi:[1,0,0]
	v_pk_fma_f32 v[172:173], v[172:173], 0.5, 0.5 op_sel_hi:[1,0,0]
	v_pk_mul_f32 v[174:175], v[2:3], v[174:175]
	v_pk_mul_f32 v[172:173], v[0:1], v[172:173]
	global_store_dwordx4 v[132:133], v[172:175], off offset:576
	s_cbranch_execnz .LBB0_1376
